# baseline (speedup 1.0000x reference)
.LBB0_26:
	s_ashr_i32 s53, s52, 31
	s_and_b32 s66, s65, 1
	s_lshl_b64 s[18:19], s[52:53], 19
	s_cmp_eq_u32 s66, 0
	v_readlane_b32 s54, v251, 5
	v_readlane_b32 s55, v251, 6
	s_cselect_b32 s53, s34, s54
	s_cselect_b32 s13, s35, s55
	s_cselect_b32 s60, s21, s45
	s_cselect_b32 s61, s22, s62
	s_add_u32 s54, s53, s18
	s_addc_u32 s55, s13, s19
	s_and_b64 s[18:19], s[4:5], exec
	s_cselect_b32 s18, s55, s25
	s_cselect_b32 s19, s54, s24
	s_ashr_i32 s13, s12, 31
	s_lshl_b64 s[56:57], s[12:13], 19
	s_add_u32 s56, s60, s56
	s_addc_u32 s57, s61, s57
	s_and_b64 s[60:61], s[4:5], exec
	s_cselect_b32 s13, s57, s59
	s_cselect_b32 s53, s56, s58
	s_add_u32 s24, s24, 0x40080
	s_addc_u32 s25, s25, 0
	s_add_u32 s76, s58, 0x100
	s_addc_u32 s77, s59, 0
	s_mov_b32 s84, -2
	v_add_u32_e32 v234, 0x10000, v209
	v_add_u32_e32 v235, 0x14000, v209
	v_add_u32_e32 v236, 0x18000, v209
	v_add_u32_e32 v237, 0x1c000, v209
.LBB0_27:
	s_add_u32 s58, s24, 0xfffc0080
	s_addc_u32 s59, s25, -1
	s_add_i32 s80, 0, 0x10000
	s_cmp_eq_u32 s84, 12
	s_cselect_b32 s61, s18, s59
	s_cselect_b32 s60, s19, s58
	s_cselect_b32 s59, s13, s77
	s_cselect_b32 s58, s53, s76
	s_add_i32 s81, 0, 0x14000
	ds_read_b128 v[130:133], v234
	ds_read_b128 v[134:137], v234 offset:1024
	ds_read_b128 v[138:141], v234 offset:2048
	ds_read_b128 v[142:145], v234 offset:3072
	ds_read_b128 v[146:149], v235
	ds_read_b128 v[150:153], v235 offset:1024
	ds_read_b128 v[154:157], v235 offset:2048
	ds_read_b128 v[158:161], v235 offset:3072
	s_add_i32 m0, s16, 0xc000
	ds_read_b128 v[162:165], v211
	ds_read_b128 v[166:169], v211 offset:1024
	ds_read_b128 v[170:173], v211 offset:2048
	ds_read_b128 v[174:177], v211 offset:3072
	ds_read_b128 v[178:181], v211 offset:4096
	ds_read_b128 v[182:185], v211 offset:5120
	ds_read_b128 v[212:215], v211 offset:6144
	ds_read_b128 v[216:219], v211 offset:7168
	global_load_lds_dwordx4 v202, s[24:25]
	s_add_i32 m0, s16, 0xe000
	s_nop 0
	global_load_lds_dwordx4 v204, s[24:25]
	s_waitcnt vmcnt(8)
	s_waitcnt lgkmcnt(0)
	s_barrier
	s_setprio 1
	s_waitcnt lgkmcnt(0)
	v_mfma_f32_16x16x32_bf16 v[124:127], v[130:133], v[162:165], v[124:127]
	v_mfma_f32_16x16x32_bf16 v[120:123], v[138:141], v[162:165], v[120:123]
	v_mfma_f32_16x16x32_bf16 v[116:119], v[130:133], v[170:173], v[116:119]
	v_mfma_f32_16x16x32_bf16 v[112:115], v[138:141], v[170:173], v[112:115]
	v_mfma_f32_16x16x32_bf16 v[108:111], v[130:133], v[178:181], v[108:111]
	v_mfma_f32_16x16x32_bf16 v[104:107], v[138:141], v[178:181], v[104:107]
	v_mfma_f32_16x16x32_bf16 v[100:103], v[130:133], v[212:215], v[100:103]
	v_mfma_f32_16x16x32_bf16 v[96:99], v[138:141], v[212:215], v[96:99]
	v_mfma_f32_16x16x32_bf16 v[124:127], v[134:137], v[166:169], v[124:127]
	v_mfma_f32_16x16x32_bf16 v[120:123], v[142:145], v[166:169], v[120:123]
	v_mfma_f32_16x16x32_bf16 v[116:119], v[134:137], v[174:177], v[116:119]
	v_mfma_f32_16x16x32_bf16 v[112:115], v[142:145], v[174:177], v[112:115]
	v_mfma_f32_16x16x32_bf16 v[108:111], v[134:137], v[182:185], v[108:111]
	v_mfma_f32_16x16x32_bf16 v[104:107], v[142:145], v[182:185], v[104:107]
	v_mfma_f32_16x16x32_bf16 v[100:103], v[134:137], v[216:219], v[100:103]
	v_mfma_f32_16x16x32_bf16 v[96:99], v[142:145], v[216:219], v[96:99]
	s_setprio 0
	s_setprio 1
	v_mfma_f32_16x16x32_bf16 v[92:95], v[146:149], v[162:165], v[92:95]
	v_mfma_f32_16x16x32_bf16 v[88:91], v[154:157], v[162:165], v[88:91]
	v_mfma_f32_16x16x32_bf16 v[84:87], v[146:149], v[170:173], v[84:87]
	v_mfma_f32_16x16x32_bf16 v[80:83], v[154:157], v[170:173], v[80:83]
	v_mfma_f32_16x16x32_bf16 v[76:79], v[146:149], v[178:181], v[76:79]
	v_mfma_f32_16x16x32_bf16 v[72:75], v[154:157], v[178:181], v[72:75]
	v_mfma_f32_16x16x32_bf16 v[68:71], v[146:149], v[212:215], v[68:71]
	v_mfma_f32_16x16x32_bf16 v[64:67], v[154:157], v[212:215], v[64:67]
	v_mfma_f32_16x16x32_bf16 v[92:95], v[150:153], v[166:169], v[92:95]
	v_mfma_f32_16x16x32_bf16 v[88:91], v[158:161], v[166:169], v[88:91]
	v_mfma_f32_16x16x32_bf16 v[84:87], v[150:153], v[174:177], v[84:87]
	v_mfma_f32_16x16x32_bf16 v[80:83], v[158:161], v[174:177], v[80:83]
	v_mfma_f32_16x16x32_bf16 v[76:79], v[150:153], v[182:185], v[76:79]
	v_mfma_f32_16x16x32_bf16 v[72:75], v[158:161], v[182:185], v[72:75]
	v_mfma_f32_16x16x32_bf16 v[68:71], v[150:153], v[216:219], v[68:71]
	v_mfma_f32_16x16x32_bf16 v[64:67], v[158:161], v[216:219], v[64:67]
	s_setprio 0
	s_barrier
	s_add_i32 s80, s80, s33
	s_mov_b32 m0, s80
	ds_read_b128 v[162:165], v211 offset:16384
	ds_read_b128 v[166:169], v211 offset:17408
	ds_read_b128 v[170:173], v211 offset:18432
	ds_read_b128 v[174:177], v211 offset:19456
	ds_read_b128 v[178:181], v211 offset:20480
	ds_read_b128 v[182:185], v211 offset:21504
	ds_read_b128 v[212:215], v211 offset:22528
	ds_read_b128 v[216:219], v211 offset:23552
	global_load_lds_dwordx4 v196, s[58:59]
	s_add_i32 m0, s80, 0x2000
	s_add_u32 s96, s58, 0x40000
	s_addc_u32 s97, s59, 0
	s_add_i32 s80, s81, s33
	global_load_lds_dwordx4 v192, s[58:59]
	s_mov_b32 m0, s80
	s_nop 0
	global_load_lds_dwordx4 v196, s[96:97]
	s_add_i32 m0, s80, 0x2000
	s_nop 0
	global_load_lds_dwordx4 v192, s[96:97]
	s_mov_b32 m0, s16
	s_nop 0
	global_load_lds_dwordx4 v198, s[60:61]
	s_mov_b32 m0, s17
	s_nop 0
	global_load_lds_dwordx4 v194, s[60:61]
	s_add_u32 s100, s60, 0x80
	s_addc_u32 s101, s61, 0
	s_waitcnt vmcnt(8)
	s_waitcnt lgkmcnt(0)
	s_barrier
	s_setprio 1
	s_waitcnt lgkmcnt(0)
	v_mfma_f32_16x16x32_bf16 v[60:63], v[130:133], v[162:165], v[60:63]
	v_mfma_f32_16x16x32_bf16 v[56:59], v[138:141], v[162:165], v[56:59]
	v_mfma_f32_16x16x32_bf16 v[52:55], v[130:133], v[170:173], v[52:55]
	v_mfma_f32_16x16x32_bf16 v[48:51], v[138:141], v[170:173], v[48:51]
	v_mfma_f32_16x16x32_bf16 v[44:47], v[130:133], v[178:181], v[44:47]
	v_mfma_f32_16x16x32_bf16 v[40:43], v[138:141], v[178:181], v[40:43]
	v_mfma_f32_16x16x32_bf16 v[36:39], v[130:133], v[212:215], v[36:39]
	v_mfma_f32_16x16x32_bf16 v[32:35], v[138:141], v[212:215], v[32:35]
	v_mfma_f32_16x16x32_bf16 v[60:63], v[134:137], v[166:169], v[60:63]
	v_mfma_f32_16x16x32_bf16 v[56:59], v[142:145], v[166:169], v[56:59]
	v_mfma_f32_16x16x32_bf16 v[52:55], v[134:137], v[174:177], v[52:55]
	v_mfma_f32_16x16x32_bf16 v[48:51], v[142:145], v[174:177], v[48:51]
	v_mfma_f32_16x16x32_bf16 v[44:47], v[134:137], v[182:185], v[44:47]
	v_mfma_f32_16x16x32_bf16 v[40:43], v[142:145], v[182:185], v[40:43]
	v_mfma_f32_16x16x32_bf16 v[36:39], v[134:137], v[216:219], v[36:39]
	v_mfma_f32_16x16x32_bf16 v[32:35], v[142:145], v[216:219], v[32:35]
	s_setprio 0
	s_setprio 1
	v_mfma_f32_16x16x32_bf16 v[28:31], v[146:149], v[162:165], v[28:31]
	v_mfma_f32_16x16x32_bf16 v[24:27], v[154:157], v[162:165], v[24:27]
	v_mfma_f32_16x16x32_bf16 v[20:23], v[146:149], v[170:173], v[20:23]
	v_mfma_f32_16x16x32_bf16 v[16:19], v[154:157], v[170:173], v[16:19]
	v_mfma_f32_16x16x32_bf16 v[12:15], v[146:149], v[178:181], v[12:15]
	v_mfma_f32_16x16x32_bf16 v[8:11], v[154:157], v[178:181], v[8:11]
	v_mfma_f32_16x16x32_bf16 v[4:7], v[146:149], v[212:215], v[4:7]
	v_mfma_f32_16x16x32_bf16 v[0:3], v[154:157], v[212:215], v[0:3]
	v_mfma_f32_16x16x32_bf16 v[28:31], v[150:153], v[166:169], v[28:31]
	v_mfma_f32_16x16x32_bf16 v[24:27], v[158:161], v[166:169], v[24:27]
	v_mfma_f32_16x16x32_bf16 v[20:23], v[150:153], v[174:177], v[20:23]
	v_mfma_f32_16x16x32_bf16 v[16:19], v[158:161], v[174:177], v[16:19]
	v_mfma_f32_16x16x32_bf16 v[12:15], v[150:153], v[182:185], v[12:15]
	v_mfma_f32_16x16x32_bf16 v[8:11], v[158:161], v[182:185], v[8:11]
	v_mfma_f32_16x16x32_bf16 v[4:7], v[150:153], v[216:219], v[4:7]
	v_mfma_f32_16x16x32_bf16 v[0:3], v[158:161], v[216:219], v[0:3]
	s_setprio 0
	s_barrier
	s_add_i32 s80, 0, 0x18000
	s_add_i32 s81, 0, 0x1c000
	ds_read_b128 v[130:133], v236
	ds_read_b128 v[134:137], v236 offset:1024
	ds_read_b128 v[138:141], v236 offset:2048
	ds_read_b128 v[142:145], v236 offset:3072
	ds_read_b128 v[146:149], v237
	ds_read_b128 v[150:153], v237 offset:1024
	ds_read_b128 v[154:157], v237 offset:2048
	ds_read_b128 v[158:161], v237 offset:3072
	s_add_u32 s60, s60, 0x40000
	s_addc_u32 s61, s61, 0
	s_mov_b32 m0, s23
	ds_read_b128 v[162:165], v211 offset:32768
	ds_read_b128 v[166:169], v211 offset:33792
	ds_read_b128 v[170:173], v211 offset:34816
	ds_read_b128 v[174:177], v211 offset:35840
	ds_read_b128 v[178:181], v211 offset:36864
	ds_read_b128 v[182:185], v211 offset:37888
	ds_read_b128 v[212:215], v211 offset:38912
	ds_read_b128 v[216:219], v211 offset:39936
	global_load_lds_dwordx4 v198, s[60:61]
	s_mov_b32 m0, s44
	s_nop 0
	global_load_lds_dwordx4 v194, s[60:61]
	s_waitcnt vmcnt(8)
	s_waitcnt lgkmcnt(0)
	s_barrier
	s_setprio 1
	s_waitcnt lgkmcnt(0)
	v_mfma_f32_16x16x32_bf16 v[124:127], v[130:133], v[162:165], v[124:127]
	v_mfma_f32_16x16x32_bf16 v[120:123], v[138:141], v[162:165], v[120:123]
	v_mfma_f32_16x16x32_bf16 v[116:119], v[130:133], v[170:173], v[116:119]
	v_mfma_f32_16x16x32_bf16 v[112:115], v[138:141], v[170:173], v[112:115]
	v_mfma_f32_16x16x32_bf16 v[108:111], v[130:133], v[178:181], v[108:111]
	v_mfma_f32_16x16x32_bf16 v[104:107], v[138:141], v[178:181], v[104:107]
	v_mfma_f32_16x16x32_bf16 v[100:103], v[130:133], v[212:215], v[100:103]
	v_mfma_f32_16x16x32_bf16 v[96:99], v[138:141], v[212:215], v[96:99]
	v_mfma_f32_16x16x32_bf16 v[124:127], v[134:137], v[166:169], v[124:127]
	v_mfma_f32_16x16x32_bf16 v[120:123], v[142:145], v[166:169], v[120:123]
	v_mfma_f32_16x16x32_bf16 v[116:119], v[134:137], v[174:177], v[116:119]
	v_mfma_f32_16x16x32_bf16 v[112:115], v[142:145], v[174:177], v[112:115]
	v_mfma_f32_16x16x32_bf16 v[108:111], v[134:137], v[182:185], v[108:111]
	v_mfma_f32_16x16x32_bf16 v[104:107], v[142:145], v[182:185], v[104:107]
	v_mfma_f32_16x16x32_bf16 v[100:103], v[134:137], v[216:219], v[100:103]
	v_mfma_f32_16x16x32_bf16 v[96:99], v[142:145], v[216:219], v[96:99]
	s_setprio 0
	s_setprio 1
	v_mfma_f32_16x16x32_bf16 v[92:95], v[146:149], v[162:165], v[92:95]
	v_mfma_f32_16x16x32_bf16 v[88:91], v[154:157], v[162:165], v[88:91]
	v_mfma_f32_16x16x32_bf16 v[84:87], v[146:149], v[170:173], v[84:87]
	v_mfma_f32_16x16x32_bf16 v[80:83], v[154:157], v[170:173], v[80:83]
	v_mfma_f32_16x16x32_bf16 v[76:79], v[146:149], v[178:181], v[76:79]
	v_mfma_f32_16x16x32_bf16 v[72:75], v[154:157], v[178:181], v[72:75]
	v_mfma_f32_16x16x32_bf16 v[68:71], v[146:149], v[212:215], v[68:71]
	v_mfma_f32_16x16x32_bf16 v[64:67], v[154:157], v[212:215], v[64:67]
	v_mfma_f32_16x16x32_bf16 v[92:95], v[150:153], v[166:169], v[92:95]
	v_mfma_f32_16x16x32_bf16 v[88:91], v[158:161], v[166:169], v[88:91]
	v_mfma_f32_16x16x32_bf16 v[84:87], v[150:153], v[174:177], v[84:87]
	v_mfma_f32_16x16x32_bf16 v[80:83], v[158:161], v[174:177], v[80:83]
	v_mfma_f32_16x16x32_bf16 v[76:79], v[150:153], v[182:185], v[76:79]
	v_mfma_f32_16x16x32_bf16 v[72:75], v[158:161], v[182:185], v[72:75]
	v_mfma_f32_16x16x32_bf16 v[68:71], v[150:153], v[216:219], v[68:71]
	v_mfma_f32_16x16x32_bf16 v[64:67], v[158:161], v[216:219], v[64:67]
	s_setprio 0
	s_barrier
	s_add_i32 s60, s80, s33
	s_add_u32 s58, s58, 0x80
	s_addc_u32 s59, s59, 0
	s_mov_b32 m0, s60
	ds_read_b128 v[162:165], v211 offset:49152
	ds_read_b128 v[166:169], v211 offset:50176
	ds_read_b128 v[170:173], v211 offset:51200
	ds_read_b128 v[174:177], v211 offset:52224
	ds_read_b128 v[178:181], v211 offset:53248
	ds_read_b128 v[182:185], v211 offset:54272
	ds_read_b128 v[212:215], v211 offset:55296
	ds_read_b128 v[216:219], v211 offset:56320
	global_load_lds_dwordx4 v196, s[58:59]
	s_add_i32 m0, s60, 0x2000
	s_add_i32 s60, s81, s33
	global_load_lds_dwordx4 v192, s[58:59]
	s_add_u32 s58, s58, 0x40000
	s_addc_u32 s59, s59, 0
	s_mov_b32 m0, s60
	s_nop 0
	global_load_lds_dwordx4 v196, s[58:59]
	s_add_i32 m0, s60, 0x2000
	s_nop 0
	global_load_lds_dwordx4 v192, s[58:59]
	s_mov_b32 m0, s63
	s_nop 0
	global_load_lds_dwordx4 v198, s[100:101]
	s_mov_b32 m0, s64
	s_nop 0
	global_load_lds_dwordx4 v194, s[100:101]
	s_waitcnt vmcnt(8)
	s_waitcnt lgkmcnt(0)
	s_barrier
	s_setprio 1
	s_waitcnt lgkmcnt(0)
	v_mfma_f32_16x16x32_bf16 v[60:63], v[130:133], v[162:165], v[60:63]
	v_mfma_f32_16x16x32_bf16 v[56:59], v[138:141], v[162:165], v[56:59]
	v_mfma_f32_16x16x32_bf16 v[52:55], v[130:133], v[170:173], v[52:55]
	v_mfma_f32_16x16x32_bf16 v[48:51], v[138:141], v[170:173], v[48:51]
	v_mfma_f32_16x16x32_bf16 v[44:47], v[130:133], v[178:181], v[44:47]
	v_mfma_f32_16x16x32_bf16 v[40:43], v[138:141], v[178:181], v[40:43]
	v_mfma_f32_16x16x32_bf16 v[36:39], v[130:133], v[212:215], v[36:39]
	v_mfma_f32_16x16x32_bf16 v[32:35], v[138:141], v[212:215], v[32:35]
	v_mfma_f32_16x16x32_bf16 v[60:63], v[134:137], v[166:169], v[60:63]
	v_mfma_f32_16x16x32_bf16 v[56:59], v[142:145], v[166:169], v[56:59]
	v_mfma_f32_16x16x32_bf16 v[52:55], v[134:137], v[174:177], v[52:55]
	v_mfma_f32_16x16x32_bf16 v[48:51], v[142:145], v[174:177], v[48:51]
	v_mfma_f32_16x16x32_bf16 v[44:47], v[134:137], v[182:185], v[44:47]
	v_mfma_f32_16x16x32_bf16 v[40:43], v[142:145], v[182:185], v[40:43]
	v_mfma_f32_16x16x32_bf16 v[36:39], v[134:137], v[216:219], v[36:39]
	v_mfma_f32_16x16x32_bf16 v[32:35], v[142:145], v[216:219], v[32:35]
	s_setprio 0
	s_setprio 1
	v_mfma_f32_16x16x32_bf16 v[28:31], v[146:149], v[162:165], v[28:31]
	v_mfma_f32_16x16x32_bf16 v[24:27], v[154:157], v[162:165], v[24:27]
	v_mfma_f32_16x16x32_bf16 v[20:23], v[146:149], v[170:173], v[20:23]
	v_mfma_f32_16x16x32_bf16 v[16:19], v[154:157], v[170:173], v[16:19]
	v_mfma_f32_16x16x32_bf16 v[12:15], v[146:149], v[178:181], v[12:15]
	v_mfma_f32_16x16x32_bf16 v[8:11], v[154:157], v[178:181], v[8:11]
	v_mfma_f32_16x16x32_bf16 v[4:7], v[146:149], v[212:215], v[4:7]
	v_mfma_f32_16x16x32_bf16 v[0:3], v[154:157], v[212:215], v[0:3]
	v_mfma_f32_16x16x32_bf16 v[28:31], v[150:153], v[166:169], v[28:31]
	v_mfma_f32_16x16x32_bf16 v[24:27], v[158:161], v[166:169], v[24:27]
	v_mfma_f32_16x16x32_bf16 v[20:23], v[150:153], v[174:177], v[20:23]
	v_mfma_f32_16x16x32_bf16 v[16:19], v[158:161], v[174:177], v[16:19]
	v_mfma_f32_16x16x32_bf16 v[12:15], v[150:153], v[182:185], v[12:15]
	v_mfma_f32_16x16x32_bf16 v[8:11], v[158:161], v[182:185], v[8:11]
	v_mfma_f32_16x16x32_bf16 v[4:7], v[150:153], v[216:219], v[4:7]
	v_mfma_f32_16x16x32_bf16 v[0:3], v[158:161], v[216:219], v[0:3]
	s_setprio 0
	s_barrier
	s_add_i32 s84, s84, 2
	s_add_u32 s24, s24, 0x100
	s_addc_u32 s25, s25, 0
	s_add_u32 s76, s76, 0x100
	s_addc_u32 s77, s77, 0
	s_cmp_gt_u32 s84, 13
	s_cbranch_scc0 .LBB0_27
	s_and_b64 vcc, exec, s[10:11]
	s_cbranch_vccz .LBB0_30
	s_barrier

.LBB0_113:
	s_ashr_i32 s77, s76, 31
	s_lshl_b64 s[18:19], s[76:77], 20
	s_add_u32 s54, s34, s18
	s_addc_u32 s55, s35, s19
	s_and_b64 s[18:19], s[10:11], exec
	s_cselect_b32 s3, s55, s1
	s_cselect_b32 s13, s54, s0
	s_ashr_i32 s87, s86, 31
	s_lshl_b64 s[18:19], s[86:87], 20
	s_add_u32 s28, s44, s18
	s_addc_u32 s29, s17, s19
	s_and_b64 s[18:19], s[10:11], exec
	s_cselect_b32 s18, s29, s67
	s_cselect_b32 s19, s28, s66
	s_add_u32 s0, s0, 0x80080
	s_addc_u32 s1, s1, 0
	s_add_u32 s59, s66, 0x100
	v_mov_b32_e32 v0, 0
	s_addc_u32 s61, s67, 0
	s_mov_b32 s90, -2
	v_mov_b32_e32 v1, v0
	v_mov_b32_e32 v2, v0
	v_mov_b32_e32 v3, v0
	v_mov_b32_e32 v4, v0
	v_mov_b32_e32 v5, v0
	v_mov_b32_e32 v6, v0
	v_mov_b32_e32 v7, v0
	v_mov_b32_e32 v16, v0
	v_mov_b32_e32 v17, v0
	v_mov_b32_e32 v18, v0
	v_mov_b32_e32 v19, v0
	v_mov_b32_e32 v20, v0
	v_mov_b32_e32 v21, v0
	v_mov_b32_e32 v22, v0
	v_mov_b32_e32 v23, v0
	v_mov_b32_e32 v32, v0
	v_mov_b32_e32 v33, v0
	v_mov_b32_e32 v34, v0
	v_mov_b32_e32 v35, v0
	v_mov_b32_e32 v36, v0
	v_mov_b32_e32 v37, v0
	v_mov_b32_e32 v38, v0
	v_mov_b32_e32 v39, v0
	v_mov_b32_e32 v48, v0
	v_mov_b32_e32 v49, v0
	v_mov_b32_e32 v50, v0
	v_mov_b32_e32 v51, v0
	v_mov_b32_e32 v52, v0
	v_mov_b32_e32 v53, v0
	v_mov_b32_e32 v54, v0
	v_mov_b32_e32 v55, v0
	v_mov_b32_e32 v8, v0
	v_mov_b32_e32 v9, v0
	v_mov_b32_e32 v10, v0
	v_mov_b32_e32 v11, v0
	v_mov_b32_e32 v12, v0
	v_mov_b32_e32 v13, v0
	v_mov_b32_e32 v14, v0
	v_mov_b32_e32 v15, v0
	v_mov_b32_e32 v24, v0
	v_mov_b32_e32 v25, v0
	v_mov_b32_e32 v26, v0
	v_mov_b32_e32 v27, v0
	v_mov_b32_e32 v28, v0
	v_mov_b32_e32 v29, v0
	v_mov_b32_e32 v30, v0
	v_mov_b32_e32 v31, v0
	v_mov_b32_e32 v40, v0
	v_mov_b32_e32 v41, v0
	v_mov_b32_e32 v42, v0
	v_mov_b32_e32 v43, v0
	v_mov_b32_e32 v44, v0
	v_mov_b32_e32 v45, v0
	v_mov_b32_e32 v46, v0
	v_mov_b32_e32 v47, v0
	v_mov_b32_e32 v56, v0
	v_mov_b32_e32 v57, v0
	v_mov_b32_e32 v58, v0
	v_mov_b32_e32 v59, v0
	v_mov_b32_e32 v60, v0
	v_mov_b32_e32 v61, v0
	v_mov_b32_e32 v62, v0
	v_mov_b32_e32 v63, v0
	s_waitcnt vmcnt(0)
	v_mov_b32_e32 v64, v0
	v_mov_b32_e32 v65, v0
	v_mov_b32_e32 v66, v0
	v_mov_b32_e32 v67, v0
	v_mov_b32_e32 v68, v0
	v_mov_b32_e32 v69, v0
	v_mov_b32_e32 v70, v0
	v_mov_b32_e32 v71, v0
	v_mov_b32_e32 v80, v0
	v_mov_b32_e32 v81, v0
	v_mov_b32_e32 v82, v0
	v_mov_b32_e32 v83, v0
	v_mov_b32_e32 v84, v0
	v_mov_b32_e32 v85, v0
	v_mov_b32_e32 v86, v0
	v_mov_b32_e32 v87, v0
	v_mov_b32_e32 v96, v0
	v_mov_b32_e32 v97, v0
	v_mov_b32_e32 v98, v0
	v_mov_b32_e32 v99, v0
	v_mov_b32_e32 v100, v0
	v_mov_b32_e32 v101, v0
	v_mov_b32_e32 v102, v0
	v_mov_b32_e32 v103, v0
	v_mov_b32_e32 v112, v0
	v_mov_b32_e32 v113, v0
	v_mov_b32_e32 v114, v0
	v_mov_b32_e32 v115, v0
	v_mov_b32_e32 v116, v0
	v_mov_b32_e32 v117, v0
	v_mov_b32_e32 v118, v0
	v_mov_b32_e32 v119, v0
	v_mov_b32_e32 v72, v0
	v_mov_b32_e32 v73, v0
	v_mov_b32_e32 v74, v0
	v_mov_b32_e32 v75, v0
	v_mov_b32_e32 v76, v0
	v_mov_b32_e32 v77, v0
	v_mov_b32_e32 v78, v0
	v_mov_b32_e32 v79, v0
	v_mov_b32_e32 v88, v0
	v_mov_b32_e32 v89, v0
	v_mov_b32_e32 v90, v0
	v_mov_b32_e32 v91, v0
	v_mov_b32_e32 v92, v0
	v_mov_b32_e32 v93, v0
	v_mov_b32_e32 v94, v0
	v_mov_b32_e32 v95, v0
	v_mov_b32_e32 v104, v0
	v_mov_b32_e32 v105, v0
	v_mov_b32_e32 v106, v0
	v_mov_b32_e32 v107, v0
	v_mov_b32_e32 v108, v0
	v_mov_b32_e32 v109, v0
	v_mov_b32_e32 v110, v0
	v_mov_b32_e32 v111, v0
	v_mov_b32_e32 v120, v0
	v_mov_b32_e32 v121, v0
	v_mov_b32_e32 v122, v0
	v_mov_b32_e32 v123, v0
	v_mov_b32_e32 v124, v0
	v_mov_b32_e32 v125, v0
	v_mov_b32_e32 v126, v0
	v_mov_b32_e32 v127, v0
	v_add_u32_e32 v234, 0x10000, v174
	v_add_u32_e32 v235, 0x14000, v174
	v_add_u32_e32 v236, 0x18000, v174
	v_add_u32_e32 v237, 0x1c000, v174
.LBB0_114:
	s_add_u32 s20, s0, 0xfff80080
	s_addc_u32 s66, s1, -1
	s_add_i32 s80, 0, 0x10000
	s_cmp_eq_u32 s90, 28
	s_cselect_b32 s97, s3, s66
	s_cselect_b32 s96, s13, s20
	s_cselect_b32 s67, s18, s61
	s_cselect_b32 s66, s19, s59
	s_add_i32 s20, 0, 0x14000
	ds_read_b128 v[130:133], v234
	ds_read_b128 v[134:137], v234 offset:1024
	ds_read_b128 v[152:155], v234 offset:2048
	ds_read_b128 v[156:159], v234 offset:3072
	ds_read_b128 v[160:163], v235
	ds_read_b128 v[164:167], v235 offset:1024
	ds_read_b128 v[168:171], v235 offset:2048
	ds_read_b128 v[178:181], v235 offset:3072
	s_add_i32 m0, s25, 0xc000
	ds_read_b128 v[182:185], v176
	ds_read_b128 v[192:195], v176 offset:1024
	ds_read_b128 v[196:199], v176 offset:2048
	ds_read_b128 v[200:203], v176 offset:3072
	ds_read_b128 v[204:207], v176 offset:4096
	ds_read_b128 v[208:211], v176 offset:5120
	ds_read_b128 v[212:215], v176 offset:6144
	ds_read_b128 v[216:219], v176 offset:7168
	global_load_lds_dwordx4 v148, s[0:1]
	s_add_i32 m0, s25, 0xe000
	s_nop 0
	global_load_lds_dwordx4 v150, s[0:1]
	s_waitcnt vmcnt(8)
	s_waitcnt lgkmcnt(0)
	s_barrier
	s_setprio 1
	s_waitcnt lgkmcnt(0)
	v_mfma_f32_16x16x32_bf16 v[124:127], v[130:133], v[182:185], v[124:127]
	v_mfma_f32_16x16x32_bf16 v[120:123], v[152:155], v[182:185], v[120:123]
	v_mfma_f32_16x16x32_bf16 v[108:111], v[130:133], v[196:199], v[108:111]
	v_mfma_f32_16x16x32_bf16 v[104:107], v[152:155], v[196:199], v[104:107]
	v_mfma_f32_16x16x32_bf16 v[92:95], v[130:133], v[204:207], v[92:95]
	v_mfma_f32_16x16x32_bf16 v[88:91], v[152:155], v[204:207], v[88:91]
	v_mfma_f32_16x16x32_bf16 v[76:79], v[130:133], v[212:215], v[76:79]
	v_mfma_f32_16x16x32_bf16 v[72:75], v[152:155], v[212:215], v[72:75]
	v_mfma_f32_16x16x32_bf16 v[124:127], v[134:137], v[192:195], v[124:127]
	v_mfma_f32_16x16x32_bf16 v[120:123], v[156:159], v[192:195], v[120:123]
	v_mfma_f32_16x16x32_bf16 v[108:111], v[134:137], v[200:203], v[108:111]
	v_mfma_f32_16x16x32_bf16 v[104:107], v[156:159], v[200:203], v[104:107]
	v_mfma_f32_16x16x32_bf16 v[92:95], v[134:137], v[208:211], v[92:95]
	v_mfma_f32_16x16x32_bf16 v[88:91], v[156:159], v[208:211], v[88:91]
	v_mfma_f32_16x16x32_bf16 v[76:79], v[134:137], v[216:219], v[76:79]
	v_mfma_f32_16x16x32_bf16 v[72:75], v[156:159], v[216:219], v[72:75]
	s_setprio 0
	s_setprio 1
	v_mfma_f32_16x16x32_bf16 v[116:119], v[160:163], v[182:185], v[116:119]
	v_mfma_f32_16x16x32_bf16 v[112:115], v[168:171], v[182:185], v[112:115]
	v_mfma_f32_16x16x32_bf16 v[100:103], v[160:163], v[196:199], v[100:103]
	v_mfma_f32_16x16x32_bf16 v[96:99], v[168:171], v[196:199], v[96:99]
	v_mfma_f32_16x16x32_bf16 v[84:87], v[160:163], v[204:207], v[84:87]
	v_mfma_f32_16x16x32_bf16 v[80:83], v[168:171], v[204:207], v[80:83]
	v_mfma_f32_16x16x32_bf16 v[68:71], v[160:163], v[212:215], v[68:71]
	v_mfma_f32_16x16x32_bf16 v[64:67], v[168:171], v[212:215], v[64:67]
	v_mfma_f32_16x16x32_bf16 v[116:119], v[164:167], v[192:195], v[116:119]
	v_mfma_f32_16x16x32_bf16 v[112:115], v[178:181], v[192:195], v[112:115]
	v_mfma_f32_16x16x32_bf16 v[100:103], v[164:167], v[200:203], v[100:103]
	v_mfma_f32_16x16x32_bf16 v[96:99], v[178:181], v[200:203], v[96:99]
	v_mfma_f32_16x16x32_bf16 v[84:87], v[164:167], v[208:211], v[84:87]
	v_mfma_f32_16x16x32_bf16 v[80:83], v[178:181], v[208:211], v[80:83]
	v_mfma_f32_16x16x32_bf16 v[68:71], v[164:167], v[216:219], v[68:71]
	v_mfma_f32_16x16x32_bf16 v[64:67], v[178:181], v[216:219], v[64:67]
	s_setprio 0
	s_barrier
	s_add_i32 s80, s80, s33
	s_mov_b32 m0, s80
	ds_read_b128 v[182:185], v176 offset:16384
	ds_read_b128 v[192:195], v176 offset:17408
	ds_read_b128 v[196:199], v176 offset:18432
	ds_read_b128 v[200:203], v176 offset:19456
	ds_read_b128 v[204:207], v176 offset:20480
	ds_read_b128 v[208:211], v176 offset:21504
	ds_read_b128 v[212:215], v176 offset:22528
	ds_read_b128 v[216:219], v176 offset:23552
	global_load_lds_dwordx4 v140, s[66:67]
	s_add_i32 m0, s80, 0x2000
	s_add_u32 vcc_lo, s66, 0x80000
	s_addc_u32 vcc_hi, s67, 0
	s_add_i32 s20, s20, s33
	global_load_lds_dwordx4 v144, s[66:67]
	s_mov_b32 m0, s20
	s_nop 0
	global_load_lds_dwordx4 v140, vcc
	s_add_i32 m0, s20, 0x2000
	s_nop 0
	global_load_lds_dwordx4 v144, vcc
	s_mov_b32 m0, s25
	s_nop 0
	global_load_lds_dwordx4 v138, s[96:97]
	s_mov_b32 m0, s21
	s_nop 0
	global_load_lds_dwordx4 v142, s[96:97]
	s_add_u32 s100, s96, 0x80
	s_addc_u32 s101, s97, 0
	s_waitcnt vmcnt(8)
	s_waitcnt lgkmcnt(0)
	s_barrier
	s_setprio 1
	s_waitcnt lgkmcnt(0)
	v_mfma_f32_16x16x32_bf16 v[60:63], v[130:133], v[182:185], v[60:63]
	v_mfma_f32_16x16x32_bf16 v[56:59], v[152:155], v[182:185], v[56:59]
	v_mfma_f32_16x16x32_bf16 v[44:47], v[130:133], v[196:199], v[44:47]
	v_mfma_f32_16x16x32_bf16 v[40:43], v[152:155], v[196:199], v[40:43]
	v_mfma_f32_16x16x32_bf16 v[28:31], v[130:133], v[204:207], v[28:31]
	v_mfma_f32_16x16x32_bf16 v[24:27], v[152:155], v[204:207], v[24:27]
	v_mfma_f32_16x16x32_bf16 v[12:15], v[130:133], v[212:215], v[12:15]
	v_mfma_f32_16x16x32_bf16 v[8:11], v[152:155], v[212:215], v[8:11]
	v_mfma_f32_16x16x32_bf16 v[60:63], v[134:137], v[192:195], v[60:63]
	v_mfma_f32_16x16x32_bf16 v[56:59], v[156:159], v[192:195], v[56:59]
	v_mfma_f32_16x16x32_bf16 v[44:47], v[134:137], v[200:203], v[44:47]
	v_mfma_f32_16x16x32_bf16 v[40:43], v[156:159], v[200:203], v[40:43]
	v_mfma_f32_16x16x32_bf16 v[28:31], v[134:137], v[208:211], v[28:31]
	v_mfma_f32_16x16x32_bf16 v[24:27], v[156:159], v[208:211], v[24:27]
	v_mfma_f32_16x16x32_bf16 v[12:15], v[134:137], v[216:219], v[12:15]
	v_mfma_f32_16x16x32_bf16 v[8:11], v[156:159], v[216:219], v[8:11]
	s_setprio 0
	s_setprio 1
	v_mfma_f32_16x16x32_bf16 v[52:55], v[160:163], v[182:185], v[52:55]
	v_mfma_f32_16x16x32_bf16 v[48:51], v[168:171], v[182:185], v[48:51]
	v_mfma_f32_16x16x32_bf16 v[36:39], v[160:163], v[196:199], v[36:39]
	v_mfma_f32_16x16x32_bf16 v[32:35], v[168:171], v[196:199], v[32:35]
	v_mfma_f32_16x16x32_bf16 v[20:23], v[160:163], v[204:207], v[20:23]
	v_mfma_f32_16x16x32_bf16 v[16:19], v[168:171], v[204:207], v[16:19]
	v_mfma_f32_16x16x32_bf16 v[4:7], v[160:163], v[212:215], v[4:7]
	v_mfma_f32_16x16x32_bf16 v[0:3], v[168:171], v[212:215], v[0:3]
	v_mfma_f32_16x16x32_bf16 v[52:55], v[164:167], v[192:195], v[52:55]
	v_mfma_f32_16x16x32_bf16 v[48:51], v[178:181], v[192:195], v[48:51]
	v_mfma_f32_16x16x32_bf16 v[36:39], v[164:167], v[200:203], v[36:39]
	v_mfma_f32_16x16x32_bf16 v[32:35], v[178:181], v[200:203], v[32:35]
	v_mfma_f32_16x16x32_bf16 v[20:23], v[164:167], v[208:211], v[20:23]
	v_mfma_f32_16x16x32_bf16 v[16:19], v[178:181], v[208:211], v[16:19]
	v_mfma_f32_16x16x32_bf16 v[4:7], v[164:167], v[216:219], v[4:7]
	v_mfma_f32_16x16x32_bf16 v[0:3], v[178:181], v[216:219], v[0:3]
	s_setprio 0
	s_barrier
	s_add_i32 s20, 0, 0x18000
	s_add_i32 s80, 0, 0x1c000
	ds_read_b128 v[130:133], v236
	ds_read_b128 v[134:137], v236 offset:1024
	ds_read_b128 v[152:155], v236 offset:2048
	ds_read_b128 v[156:159], v236 offset:3072
	ds_read_b128 v[160:163], v237
	ds_read_b128 v[164:167], v237 offset:1024
	ds_read_b128 v[168:171], v237 offset:2048
	ds_read_b128 v[178:181], v237 offset:3072
	s_add_u32 s96, s96, 0x80000
	s_addc_u32 s97, s97, 0
	s_mov_b32 m0, s22
	ds_read_b128 v[182:185], v176 offset:32768
	ds_read_b128 v[192:195], v176 offset:33792
	ds_read_b128 v[196:199], v176 offset:34816
	ds_read_b128 v[200:203], v176 offset:35840
	ds_read_b128 v[204:207], v176 offset:36864
	ds_read_b128 v[208:211], v176 offset:37888
	ds_read_b128 v[212:215], v176 offset:38912
	ds_read_b128 v[216:219], v176 offset:39936
	global_load_lds_dwordx4 v138, s[96:97]
	s_mov_b32 m0, s84
	s_nop 0
	global_load_lds_dwordx4 v142, s[96:97]
	s_waitcnt vmcnt(8)
	s_waitcnt lgkmcnt(0)
	s_barrier
	s_setprio 1
	s_waitcnt lgkmcnt(0)
	v_mfma_f32_16x16x32_bf16 v[124:127], v[130:133], v[182:185], v[124:127]
	v_mfma_f32_16x16x32_bf16 v[120:123], v[152:155], v[182:185], v[120:123]
	v_mfma_f32_16x16x32_bf16 v[108:111], v[130:133], v[196:199], v[108:111]
	v_mfma_f32_16x16x32_bf16 v[104:107], v[152:155], v[196:199], v[104:107]
	v_mfma_f32_16x16x32_bf16 v[92:95], v[130:133], v[204:207], v[92:95]
	v_mfma_f32_16x16x32_bf16 v[88:91], v[152:155], v[204:207], v[88:91]
	v_mfma_f32_16x16x32_bf16 v[76:79], v[130:133], v[212:215], v[76:79]
	v_mfma_f32_16x16x32_bf16 v[72:75], v[152:155], v[212:215], v[72:75]
	v_mfma_f32_16x16x32_bf16 v[124:127], v[134:137], v[192:195], v[124:127]
	v_mfma_f32_16x16x32_bf16 v[120:123], v[156:159], v[192:195], v[120:123]
	v_mfma_f32_16x16x32_bf16 v[108:111], v[134:137], v[200:203], v[108:111]
	v_mfma_f32_16x16x32_bf16 v[104:107], v[156:159], v[200:203], v[104:107]
	v_mfma_f32_16x16x32_bf16 v[92:95], v[134:137], v[208:211], v[92:95]
	v_mfma_f32_16x16x32_bf16 v[88:91], v[156:159], v[208:211], v[88:91]
	v_mfma_f32_16x16x32_bf16 v[76:79], v[134:137], v[216:219], v[76:79]
	v_mfma_f32_16x16x32_bf16 v[72:75], v[156:159], v[216:219], v[72:75]
	s_setprio 0
	s_setprio 1
	v_mfma_f32_16x16x32_bf16 v[116:119], v[160:163], v[182:185], v[116:119]
	v_mfma_f32_16x16x32_bf16 v[112:115], v[168:171], v[182:185], v[112:115]
	v_mfma_f32_16x16x32_bf16 v[100:103], v[160:163], v[196:199], v[100:103]
	v_mfma_f32_16x16x32_bf16 v[96:99], v[168:171], v[196:199], v[96:99]
	v_mfma_f32_16x16x32_bf16 v[84:87], v[160:163], v[204:207], v[84:87]
	v_mfma_f32_16x16x32_bf16 v[80:83], v[168:171], v[204:207], v[80:83]
	v_mfma_f32_16x16x32_bf16 v[68:71], v[160:163], v[212:215], v[68:71]
	v_mfma_f32_16x16x32_bf16 v[64:67], v[168:171], v[212:215], v[64:67]
	v_mfma_f32_16x16x32_bf16 v[116:119], v[164:167], v[192:195], v[116:119]
	v_mfma_f32_16x16x32_bf16 v[112:115], v[178:181], v[192:195], v[112:115]
	v_mfma_f32_16x16x32_bf16 v[100:103], v[164:167], v[200:203], v[100:103]
	v_mfma_f32_16x16x32_bf16 v[96:99], v[178:181], v[200:203], v[96:99]
	v_mfma_f32_16x16x32_bf16 v[84:87], v[164:167], v[208:211], v[84:87]
	v_mfma_f32_16x16x32_bf16 v[80:83], v[178:181], v[208:211], v[80:83]
	v_mfma_f32_16x16x32_bf16 v[68:71], v[164:167], v[216:219], v[68:71]
	v_mfma_f32_16x16x32_bf16 v[64:67], v[178:181], v[216:219], v[64:67]
	s_setprio 0
	s_barrier
	s_add_i32 s20, s20, s33
	s_add_u32 s66, s66, 0x80
	s_addc_u32 s67, s67, 0
	s_mov_b32 m0, s20
	ds_read_b128 v[182:185], v176 offset:49152
	ds_read_b128 v[192:195], v176 offset:50176
	ds_read_b128 v[196:199], v176 offset:51200
	ds_read_b128 v[200:203], v176 offset:52224
	ds_read_b128 v[204:207], v176 offset:53248
	ds_read_b128 v[208:211], v176 offset:54272
	ds_read_b128 v[212:215], v176 offset:55296
	ds_read_b128 v[216:219], v176 offset:56320
	global_load_lds_dwordx4 v140, s[66:67]
	s_add_i32 m0, s20, 0x2000
	s_add_i32 s20, s80, s33
	global_load_lds_dwordx4 v144, s[66:67]
	s_add_u32 s66, s66, 0x80000
	s_addc_u32 s67, s67, 0
	s_mov_b32 m0, s20
	s_nop 0
	global_load_lds_dwordx4 v140, s[66:67]
	s_add_i32 m0, s20, 0x2000
	s_nop 0
	global_load_lds_dwordx4 v144, s[66:67]
	s_mov_b32 m0, s45
	s_nop 0
	global_load_lds_dwordx4 v138, s[100:101]
	s_mov_b32 m0, s16
	s_nop 0
	global_load_lds_dwordx4 v142, s[100:101]
	s_waitcnt vmcnt(8)
	s_waitcnt lgkmcnt(0)
	s_barrier
	s_setprio 1
	s_waitcnt lgkmcnt(0)
	v_mfma_f32_16x16x32_bf16 v[60:63], v[130:133], v[182:185], v[60:63]
	v_mfma_f32_16x16x32_bf16 v[56:59], v[152:155], v[182:185], v[56:59]
	v_mfma_f32_16x16x32_bf16 v[44:47], v[130:133], v[196:199], v[44:47]
	v_mfma_f32_16x16x32_bf16 v[40:43], v[152:155], v[196:199], v[40:43]
	v_mfma_f32_16x16x32_bf16 v[28:31], v[130:133], v[204:207], v[28:31]
	v_mfma_f32_16x16x32_bf16 v[24:27], v[152:155], v[204:207], v[24:27]
	v_mfma_f32_16x16x32_bf16 v[12:15], v[130:133], v[212:215], v[12:15]
	v_mfma_f32_16x16x32_bf16 v[8:11], v[152:155], v[212:215], v[8:11]
	v_mfma_f32_16x16x32_bf16 v[60:63], v[134:137], v[192:195], v[60:63]
	v_mfma_f32_16x16x32_bf16 v[56:59], v[156:159], v[192:195], v[56:59]
	v_mfma_f32_16x16x32_bf16 v[44:47], v[134:137], v[200:203], v[44:47]
	v_mfma_f32_16x16x32_bf16 v[40:43], v[156:159], v[200:203], v[40:43]
	v_mfma_f32_16x16x32_bf16 v[28:31], v[134:137], v[208:211], v[28:31]
	v_mfma_f32_16x16x32_bf16 v[24:27], v[156:159], v[208:211], v[24:27]
	v_mfma_f32_16x16x32_bf16 v[12:15], v[134:137], v[216:219], v[12:15]
	v_mfma_f32_16x16x32_bf16 v[8:11], v[156:159], v[216:219], v[8:11]
	s_setprio 0
	s_setprio 1
	v_mfma_f32_16x16x32_bf16 v[52:55], v[160:163], v[182:185], v[52:55]
	v_mfma_f32_16x16x32_bf16 v[48:51], v[168:171], v[182:185], v[48:51]
	v_mfma_f32_16x16x32_bf16 v[36:39], v[160:163], v[196:199], v[36:39]
	v_mfma_f32_16x16x32_bf16 v[32:35], v[168:171], v[196:199], v[32:35]
	v_mfma_f32_16x16x32_bf16 v[20:23], v[160:163], v[204:207], v[20:23]
	v_mfma_f32_16x16x32_bf16 v[16:19], v[168:171], v[204:207], v[16:19]
	v_mfma_f32_16x16x32_bf16 v[4:7], v[160:163], v[212:215], v[4:7]
	v_mfma_f32_16x16x32_bf16 v[0:3], v[168:171], v[212:215], v[0:3]
	v_mfma_f32_16x16x32_bf16 v[52:55], v[164:167], v[192:195], v[52:55]
	v_mfma_f32_16x16x32_bf16 v[48:51], v[178:181], v[192:195], v[48:51]
	v_mfma_f32_16x16x32_bf16 v[36:39], v[164:167], v[200:203], v[36:39]
	v_mfma_f32_16x16x32_bf16 v[32:35], v[178:181], v[200:203], v[32:35]
	v_mfma_f32_16x16x32_bf16 v[20:23], v[164:167], v[208:211], v[20:23]
	v_mfma_f32_16x16x32_bf16 v[16:19], v[178:181], v[208:211], v[16:19]
	v_mfma_f32_16x16x32_bf16 v[4:7], v[164:167], v[216:219], v[4:7]
	v_mfma_f32_16x16x32_bf16 v[0:3], v[178:181], v[216:219], v[0:3]
	s_setprio 0
	s_barrier
	s_add_i32 s90, s90, 2
	s_add_u32 s0, s0, 0x100
	s_addc_u32 s1, s1, 0
	s_add_u32 s59, s59, 0x100
	s_addc_u32 s61, s61, 0
	s_cmp_gt_u32 s90, 29
	s_cbranch_scc0 .LBB0_114
	s_and_b64 vcc, exec, s[56:57]
	s_cbranch_vccz .LBB0_117
	s_barrier

.LBB0_231:
	s_ashr_i32 s67, s66, 31
	s_lshl_b64 s[10:11], s[66:67], 20
	v_readlane_b32 s24, v253, 14
	v_readlane_b32 s25, v253, 15
	s_add_u32 s76, s24, s10
	s_addc_u32 s77, s25, s11
	s_and_b64 s[10:11], s[4:5], exec
	s_cselect_b32 s67, s77, s7
	s_cselect_b32 s96, s76, s6
	s_ashr_i32 s65, s64, 31
	s_lshl_b64 s[10:11], s[64:65], 20
	s_add_u32 s24, s16, s10
	s_addc_u32 s25, s17, s11
	s_and_b64 s[10:11], s[4:5], exec
	s_cselect_b32 s65, s25, s9
	s_cselect_b32 s97, s24, s8
	s_add_u32 s6, s6, 0x80080
	s_addc_u32 s7, s7, 0
	s_add_u32 vcc_lo, s8, 0x100
	v_mov_b32_e32 v0, 0
	s_addc_u32 vcc_hi, s9, 0
	s_mov_b32 s20, -2
	v_mov_b32_e32 v1, v0
	v_mov_b32_e32 v2, v0
	v_mov_b32_e32 v3, v0
	v_mov_b32_e32 v4, v0
	v_mov_b32_e32 v5, v0
	v_mov_b32_e32 v6, v0
	v_mov_b32_e32 v7, v0
	v_mov_b32_e32 v16, v0
	v_mov_b32_e32 v17, v0
	v_mov_b32_e32 v18, v0
	v_mov_b32_e32 v19, v0
	v_mov_b32_e32 v20, v0
	v_mov_b32_e32 v21, v0
	v_mov_b32_e32 v22, v0
	v_mov_b32_e32 v23, v0
	v_mov_b32_e32 v32, v0
	v_mov_b32_e32 v33, v0
	v_mov_b32_e32 v34, v0
	v_mov_b32_e32 v35, v0
	v_mov_b32_e32 v36, v0
	v_mov_b32_e32 v37, v0
	v_mov_b32_e32 v38, v0
	v_mov_b32_e32 v39, v0
	v_mov_b32_e32 v48, v0
	v_mov_b32_e32 v49, v0
	v_mov_b32_e32 v50, v0
	v_mov_b32_e32 v51, v0
	v_mov_b32_e32 v52, v0
	v_mov_b32_e32 v53, v0
	v_mov_b32_e32 v54, v0
	v_mov_b32_e32 v55, v0
	v_mov_b32_e32 v8, v0
	v_mov_b32_e32 v9, v0
	v_mov_b32_e32 v10, v0
	v_mov_b32_e32 v11, v0
	v_mov_b32_e32 v12, v0
	v_mov_b32_e32 v13, v0
	v_mov_b32_e32 v14, v0
	v_mov_b32_e32 v15, v0
	v_mov_b32_e32 v24, v0
	v_mov_b32_e32 v25, v0
	v_mov_b32_e32 v26, v0
	v_mov_b32_e32 v27, v0
	v_mov_b32_e32 v28, v0
	v_mov_b32_e32 v29, v0
	v_mov_b32_e32 v30, v0
	v_mov_b32_e32 v31, v0
	v_mov_b32_e32 v40, v0
	v_mov_b32_e32 v41, v0
	v_mov_b32_e32 v42, v0
	v_mov_b32_e32 v43, v0
	v_mov_b32_e32 v44, v0
	v_mov_b32_e32 v45, v0
	v_mov_b32_e32 v46, v0
	v_mov_b32_e32 v47, v0
	v_mov_b32_e32 v56, v0
	v_mov_b32_e32 v57, v0
	v_mov_b32_e32 v58, v0
	v_mov_b32_e32 v59, v0
	v_mov_b32_e32 v60, v0
	v_mov_b32_e32 v61, v0
	v_mov_b32_e32 v62, v0
	v_mov_b32_e32 v63, v0
	s_waitcnt vmcnt(0)
	v_mov_b32_e32 v80, v0
	v_mov_b32_e32 v81, v0
	v_mov_b32_e32 v82, v0
	v_mov_b32_e32 v83, v0
	v_mov_b32_e32 v84, v0
	v_mov_b32_e32 v85, v0
	v_mov_b32_e32 v86, v0
	v_mov_b32_e32 v87, v0
	v_mov_b32_e32 v96, v0
	v_mov_b32_e32 v97, v0
	v_mov_b32_e32 v98, v0
	v_mov_b32_e32 v99, v0
	v_mov_b32_e32 v100, v0
	v_mov_b32_e32 v101, v0
	v_mov_b32_e32 v102, v0
	v_mov_b32_e32 v103, v0
	v_mov_b32_e32 v112, v0
	v_mov_b32_e32 v113, v0
	v_mov_b32_e32 v114, v0
	v_mov_b32_e32 v115, v0
	v_mov_b32_e32 v116, v0
	v_mov_b32_e32 v117, v0
	v_mov_b32_e32 v118, v0
	v_mov_b32_e32 v119, v0
	v_mov_b32_e32 v130, v0
	v_mov_b32_e32 v131, v0
	v_mov_b32_e32 v132, v0
	v_mov_b32_e32 v133, v0
	v_mov_b32_e32 v134, v0
	v_mov_b32_e32 v135, v0
	v_mov_b32_e32 v136, v0
	v_mov_b32_e32 v137, v0
	v_mov_b32_e32 v88, v0
	v_mov_b32_e32 v89, v0
	v_mov_b32_e32 v90, v0
	v_mov_b32_e32 v91, v0
	v_mov_b32_e32 v92, v0
	v_mov_b32_e32 v93, v0
	v_mov_b32_e32 v94, v0
	v_mov_b32_e32 v95, v0
	v_mov_b32_e32 v104, v0
	v_mov_b32_e32 v105, v0
	v_mov_b32_e32 v106, v0
	v_mov_b32_e32 v107, v0
	v_mov_b32_e32 v108, v0
	v_mov_b32_e32 v109, v0
	v_mov_b32_e32 v110, v0
	v_mov_b32_e32 v111, v0
	v_mov_b32_e32 v120, v0
	v_mov_b32_e32 v121, v0
	v_mov_b32_e32 v122, v0
	v_mov_b32_e32 v123, v0
	v_mov_b32_e32 v124, v0
	v_mov_b32_e32 v125, v0
	v_mov_b32_e32 v126, v0
	v_mov_b32_e32 v127, v0
	v_mov_b32_e32 v138, v0
	v_mov_b32_e32 v139, v0
	v_mov_b32_e32 v140, v0
	v_mov_b32_e32 v141, v0
	v_mov_b32_e32 v142, v0
	v_mov_b32_e32 v143, v0
	v_mov_b32_e32 v144, v0
	v_mov_b32_e32 v145, v0
	v_add_u32_e32 v234, 0x10000, v215
	v_add_u32_e32 v235, 0x14000, v215
	v_add_u32_e32 v236, 0x18000, v215
	v_add_u32_e32 v237, 0x1c000, v215
.LBB0_232:
	s_add_u32 s8, s6, 0xfff80080
	s_addc_u32 s9, s7, -1
	s_add_i32 s80, 0, 0x10000
	s_cmp_eq_u32 s20, 28
	s_cselect_b32 s11, s67, s9
	s_cselect_b32 s10, s96, s8
	s_cselect_b32 s9, s65, vcc_hi
	s_cselect_b32 s8, s97, vcc_lo
	s_add_i32 s34, 0, 0x14000
	ds_read_b128 v[64:67], v234
	ds_read_b128 v[68:71], v234 offset:1024
	ds_read_b128 v[72:75], v234 offset:2048
	ds_read_b128 v[76:79], v234 offset:3072
	ds_read_b128 v[146:149], v235
	ds_read_b128 v[150:153], v235 offset:1024
	ds_read_b128 v[154:157], v235 offset:2048
	ds_read_b128 v[158:161], v235 offset:3072
	s_add_i32 m0, s22, 0xc000
	ds_read_b128 v[162:165], v217
	ds_read_b128 v[166:169], v217 offset:1024
	ds_read_b128 v[170:173], v217 offset:2048
	ds_read_b128 v[174:177], v217 offset:3072
	ds_read_b128 v[194:197], v217 offset:4096
	ds_read_b128 v[198:201], v217 offset:5120
	ds_read_b128 v[202:205], v217 offset:6144
	ds_read_b128 v[206:209], v217 offset:7168
	global_load_lds_dwordx4 v184, s[6:7]
	s_add_i32 m0, s22, 0xe000
	s_nop 0
	global_load_lds_dwordx4 v192, s[6:7]
	s_waitcnt vmcnt(8)
	s_waitcnt lgkmcnt(0)
	s_barrier
	s_setprio 1
	s_waitcnt lgkmcnt(0)
	v_mfma_f32_16x16x32_bf16 v[142:145], v[64:67], v[162:165], v[142:145]
	v_mfma_f32_16x16x32_bf16 v[138:141], v[72:75], v[162:165], v[138:141]
	v_mfma_f32_16x16x32_bf16 v[124:127], v[64:67], v[170:173], v[124:127]
	v_mfma_f32_16x16x32_bf16 v[120:123], v[72:75], v[170:173], v[120:123]
	v_mfma_f32_16x16x32_bf16 v[108:111], v[64:67], v[194:197], v[108:111]
	v_mfma_f32_16x16x32_bf16 v[104:107], v[72:75], v[194:197], v[104:107]
	v_mfma_f32_16x16x32_bf16 v[92:95], v[64:67], v[202:205], v[92:95]
	v_mfma_f32_16x16x32_bf16 v[88:91], v[72:75], v[202:205], v[88:91]
	v_mfma_f32_16x16x32_bf16 v[142:145], v[68:71], v[166:169], v[142:145]
	v_mfma_f32_16x16x32_bf16 v[138:141], v[76:79], v[166:169], v[138:141]
	v_mfma_f32_16x16x32_bf16 v[124:127], v[68:71], v[174:177], v[124:127]
	v_mfma_f32_16x16x32_bf16 v[120:123], v[76:79], v[174:177], v[120:123]
	v_mfma_f32_16x16x32_bf16 v[108:111], v[68:71], v[198:201], v[108:111]
	v_mfma_f32_16x16x32_bf16 v[104:107], v[76:79], v[198:201], v[104:107]
	v_mfma_f32_16x16x32_bf16 v[92:95], v[68:71], v[206:209], v[92:95]
	v_mfma_f32_16x16x32_bf16 v[88:91], v[76:79], v[206:209], v[88:91]
	s_setprio 0
	s_setprio 1
	v_mfma_f32_16x16x32_bf16 v[134:137], v[146:149], v[162:165], v[134:137]
	v_mfma_f32_16x16x32_bf16 v[130:133], v[154:157], v[162:165], v[130:133]
	v_mfma_f32_16x16x32_bf16 v[116:119], v[146:149], v[170:173], v[116:119]
	v_mfma_f32_16x16x32_bf16 v[112:115], v[154:157], v[170:173], v[112:115]
	v_mfma_f32_16x16x32_bf16 v[100:103], v[146:149], v[194:197], v[100:103]
	v_mfma_f32_16x16x32_bf16 v[96:99], v[154:157], v[194:197], v[96:99]
	v_mfma_f32_16x16x32_bf16 v[84:87], v[146:149], v[202:205], v[84:87]
	v_mfma_f32_16x16x32_bf16 v[80:83], v[154:157], v[202:205], v[80:83]
	v_mfma_f32_16x16x32_bf16 v[134:137], v[150:153], v[166:169], v[134:137]
	v_mfma_f32_16x16x32_bf16 v[130:133], v[158:161], v[166:169], v[130:133]
	v_mfma_f32_16x16x32_bf16 v[116:119], v[150:153], v[174:177], v[116:119]
	v_mfma_f32_16x16x32_bf16 v[112:115], v[158:161], v[174:177], v[112:115]
	v_mfma_f32_16x16x32_bf16 v[100:103], v[150:153], v[198:201], v[100:103]
	v_mfma_f32_16x16x32_bf16 v[96:99], v[158:161], v[198:201], v[96:99]
	v_mfma_f32_16x16x32_bf16 v[84:87], v[150:153], v[206:209], v[84:87]
	v_mfma_f32_16x16x32_bf16 v[80:83], v[158:161], v[206:209], v[80:83]
	s_setprio 0
	s_barrier
	s_add_i32 s35, s80, s21
	s_mov_b32 m0, s35
	ds_read_b128 v[162:165], v217 offset:16384
	ds_read_b128 v[166:169], v217 offset:17408
	ds_read_b128 v[170:173], v217 offset:18432
	ds_read_b128 v[174:177], v217 offset:19456
	ds_read_b128 v[194:197], v217 offset:20480
	ds_read_b128 v[198:201], v217 offset:21504
	ds_read_b128 v[202:205], v217 offset:22528
	ds_read_b128 v[206:209], v217 offset:23552
	global_load_lds_dwordx4 v128, s[8:9]
	s_add_i32 m0, s35, 0x2000
	s_add_u32 s80, s8, 0x80000
	s_addc_u32 s81, s9, 0
	s_add_i32 s34, s34, s21
	global_load_lds_dwordx4 v178, s[8:9]
	s_mov_b32 m0, s34
	s_nop 0
	global_load_lds_dwordx4 v128, s[80:81]
	s_add_i32 m0, s34, 0x2000
	s_nop 0
	global_load_lds_dwordx4 v178, s[80:81]
	s_mov_b32 m0, s22
	s_nop 0
	global_load_lds_dwordx4 v182, s[10:11]
	s_mov_b32 m0, s23
	s_nop 0
	global_load_lds_dwordx4 v180, s[10:11]
	s_add_u32 s100, s10, 0x80
	s_addc_u32 s101, s11, 0
	s_waitcnt vmcnt(8)
	s_waitcnt lgkmcnt(0)
	s_barrier
	s_setprio 1
	s_waitcnt lgkmcnt(0)
	v_mfma_f32_16x16x32_bf16 v[60:63], v[64:67], v[162:165], v[60:63]
	v_mfma_f32_16x16x32_bf16 v[56:59], v[72:75], v[162:165], v[56:59]
	v_mfma_f32_16x16x32_bf16 v[44:47], v[64:67], v[170:173], v[44:47]
	v_mfma_f32_16x16x32_bf16 v[40:43], v[72:75], v[170:173], v[40:43]
	v_mfma_f32_16x16x32_bf16 v[28:31], v[64:67], v[194:197], v[28:31]
	v_mfma_f32_16x16x32_bf16 v[24:27], v[72:75], v[194:197], v[24:27]
	v_mfma_f32_16x16x32_bf16 v[12:15], v[64:67], v[202:205], v[12:15]
	v_mfma_f32_16x16x32_bf16 v[8:11], v[72:75], v[202:205], v[8:11]
	v_mfma_f32_16x16x32_bf16 v[60:63], v[68:71], v[166:169], v[60:63]
	v_mfma_f32_16x16x32_bf16 v[56:59], v[76:79], v[166:169], v[56:59]
	v_mfma_f32_16x16x32_bf16 v[44:47], v[68:71], v[174:177], v[44:47]
	v_mfma_f32_16x16x32_bf16 v[40:43], v[76:79], v[174:177], v[40:43]
	v_mfma_f32_16x16x32_bf16 v[28:31], v[68:71], v[198:201], v[28:31]
	v_mfma_f32_16x16x32_bf16 v[24:27], v[76:79], v[198:201], v[24:27]
	v_mfma_f32_16x16x32_bf16 v[12:15], v[68:71], v[206:209], v[12:15]
	v_mfma_f32_16x16x32_bf16 v[8:11], v[76:79], v[206:209], v[8:11]
	s_setprio 0
	s_setprio 1
	v_mfma_f32_16x16x32_bf16 v[52:55], v[146:149], v[162:165], v[52:55]
	v_mfma_f32_16x16x32_bf16 v[48:51], v[154:157], v[162:165], v[48:51]
	v_mfma_f32_16x16x32_bf16 v[36:39], v[146:149], v[170:173], v[36:39]
	v_mfma_f32_16x16x32_bf16 v[32:35], v[154:157], v[170:173], v[32:35]
	v_mfma_f32_16x16x32_bf16 v[20:23], v[146:149], v[194:197], v[20:23]
	v_mfma_f32_16x16x32_bf16 v[16:19], v[154:157], v[194:197], v[16:19]
	v_mfma_f32_16x16x32_bf16 v[4:7], v[146:149], v[202:205], v[4:7]
	v_mfma_f32_16x16x32_bf16 v[0:3], v[154:157], v[202:205], v[0:3]
	v_mfma_f32_16x16x32_bf16 v[52:55], v[150:153], v[166:169], v[52:55]
	v_mfma_f32_16x16x32_bf16 v[48:51], v[158:161], v[166:169], v[48:51]
	v_mfma_f32_16x16x32_bf16 v[36:39], v[150:153], v[174:177], v[36:39]
	v_mfma_f32_16x16x32_bf16 v[32:35], v[158:161], v[174:177], v[32:35]
	v_mfma_f32_16x16x32_bf16 v[20:23], v[150:153], v[198:201], v[20:23]
	v_mfma_f32_16x16x32_bf16 v[16:19], v[158:161], v[198:201], v[16:19]
	v_mfma_f32_16x16x32_bf16 v[4:7], v[150:153], v[206:209], v[4:7]
	v_mfma_f32_16x16x32_bf16 v[0:3], v[158:161], v[206:209], v[0:3]
	s_setprio 0
	s_barrier
	s_add_i32 s34, 0, 0x18000
	s_add_i32 s35, 0, 0x1c000
	ds_read_b128 v[64:67], v236
	ds_read_b128 v[68:71], v236 offset:1024
	ds_read_b128 v[72:75], v236 offset:2048
	ds_read_b128 v[76:79], v236 offset:3072
	ds_read_b128 v[146:149], v237
	ds_read_b128 v[150:153], v237 offset:1024
	ds_read_b128 v[154:157], v237 offset:2048
	ds_read_b128 v[158:161], v237 offset:3072
	s_add_u32 s10, s10, 0x80000
	s_addc_u32 s11, s11, 0
	s_mov_b32 m0, s33
	ds_read_b128 v[162:165], v217 offset:32768
	ds_read_b128 v[166:169], v217 offset:33792
	ds_read_b128 v[170:173], v217 offset:34816
	ds_read_b128 v[174:177], v217 offset:35840
	ds_read_b128 v[194:197], v217 offset:36864
	ds_read_b128 v[198:201], v217 offset:37888
	ds_read_b128 v[202:205], v217 offset:38912
	ds_read_b128 v[206:209], v217 offset:39936
	global_load_lds_dwordx4 v182, s[10:11]
	s_mov_b32 m0, s44
	s_nop 0
	global_load_lds_dwordx4 v180, s[10:11]
	s_waitcnt vmcnt(8)
	s_waitcnt lgkmcnt(0)
	s_barrier
	s_setprio 1
	s_waitcnt lgkmcnt(0)
	v_mfma_f32_16x16x32_bf16 v[142:145], v[64:67], v[162:165], v[142:145]
	v_mfma_f32_16x16x32_bf16 v[138:141], v[72:75], v[162:165], v[138:141]
	v_mfma_f32_16x16x32_bf16 v[124:127], v[64:67], v[170:173], v[124:127]
	v_mfma_f32_16x16x32_bf16 v[120:123], v[72:75], v[170:173], v[120:123]
	v_mfma_f32_16x16x32_bf16 v[108:111], v[64:67], v[194:197], v[108:111]
	v_mfma_f32_16x16x32_bf16 v[104:107], v[72:75], v[194:197], v[104:107]
	v_mfma_f32_16x16x32_bf16 v[92:95], v[64:67], v[202:205], v[92:95]
	v_mfma_f32_16x16x32_bf16 v[88:91], v[72:75], v[202:205], v[88:91]
	v_mfma_f32_16x16x32_bf16 v[142:145], v[68:71], v[166:169], v[142:145]
	v_mfma_f32_16x16x32_bf16 v[138:141], v[76:79], v[166:169], v[138:141]
	v_mfma_f32_16x16x32_bf16 v[124:127], v[68:71], v[174:177], v[124:127]
	v_mfma_f32_16x16x32_bf16 v[120:123], v[76:79], v[174:177], v[120:123]
	v_mfma_f32_16x16x32_bf16 v[108:111], v[68:71], v[198:201], v[108:111]
	v_mfma_f32_16x16x32_bf16 v[104:107], v[76:79], v[198:201], v[104:107]
	v_mfma_f32_16x16x32_bf16 v[92:95], v[68:71], v[206:209], v[92:95]
	v_mfma_f32_16x16x32_bf16 v[88:91], v[76:79], v[206:209], v[88:91]
	s_setprio 0
	s_setprio 1
	v_mfma_f32_16x16x32_bf16 v[134:137], v[146:149], v[162:165], v[134:137]
	v_mfma_f32_16x16x32_bf16 v[130:133], v[154:157], v[162:165], v[130:133]
	v_mfma_f32_16x16x32_bf16 v[116:119], v[146:149], v[170:173], v[116:119]
	v_mfma_f32_16x16x32_bf16 v[112:115], v[154:157], v[170:173], v[112:115]
	v_mfma_f32_16x16x32_bf16 v[100:103], v[146:149], v[194:197], v[100:103]
	v_mfma_f32_16x16x32_bf16 v[96:99], v[154:157], v[194:197], v[96:99]
	v_mfma_f32_16x16x32_bf16 v[84:87], v[146:149], v[202:205], v[84:87]
	v_mfma_f32_16x16x32_bf16 v[80:83], v[154:157], v[202:205], v[80:83]
	v_mfma_f32_16x16x32_bf16 v[134:137], v[150:153], v[166:169], v[134:137]
	v_mfma_f32_16x16x32_bf16 v[130:133], v[158:161], v[166:169], v[130:133]
	v_mfma_f32_16x16x32_bf16 v[116:119], v[150:153], v[174:177], v[116:119]
	v_mfma_f32_16x16x32_bf16 v[112:115], v[158:161], v[174:177], v[112:115]
	v_mfma_f32_16x16x32_bf16 v[100:103], v[150:153], v[198:201], v[100:103]
	v_mfma_f32_16x16x32_bf16 v[96:99], v[158:161], v[198:201], v[96:99]
	v_mfma_f32_16x16x32_bf16 v[84:87], v[150:153], v[206:209], v[84:87]
	v_mfma_f32_16x16x32_bf16 v[80:83], v[158:161], v[206:209], v[80:83]
	s_setprio 0
	s_barrier
	s_add_i32 s10, s34, s21
	s_add_u32 s8, s8, 0x80
	s_addc_u32 s9, s9, 0
	s_mov_b32 m0, s10
	ds_read_b128 v[162:165], v217 offset:49152
	ds_read_b128 v[166:169], v217 offset:50176
	ds_read_b128 v[170:173], v217 offset:51200
	ds_read_b128 v[174:177], v217 offset:52224
	ds_read_b128 v[194:197], v217 offset:53248
	ds_read_b128 v[198:201], v217 offset:54272
	ds_read_b128 v[202:205], v217 offset:55296
	ds_read_b128 v[206:209], v217 offset:56320
	global_load_lds_dwordx4 v128, s[8:9]
	s_add_i32 m0, s10, 0x2000
	s_add_i32 s10, s35, s21
	global_load_lds_dwordx4 v178, s[8:9]
	s_add_u32 s8, s8, 0x80000
	s_addc_u32 s9, s9, 0
	s_mov_b32 m0, s10
	s_nop 0
	global_load_lds_dwordx4 v128, s[8:9]
	s_add_i32 m0, s10, 0x2000
	s_nop 0
	global_load_lds_dwordx4 v178, s[8:9]
	s_mov_b32 m0, s1
	s_nop 0
	global_load_lds_dwordx4 v182, s[100:101]
	s_mov_b32 m0, s3
	s_nop 0
	global_load_lds_dwordx4 v180, s[100:101]
	s_waitcnt vmcnt(8)
	s_waitcnt lgkmcnt(0)
	s_barrier
	s_setprio 1
	s_waitcnt lgkmcnt(0)
	v_mfma_f32_16x16x32_bf16 v[60:63], v[64:67], v[162:165], v[60:63]
	v_mfma_f32_16x16x32_bf16 v[56:59], v[72:75], v[162:165], v[56:59]
	v_mfma_f32_16x16x32_bf16 v[44:47], v[64:67], v[170:173], v[44:47]
	v_mfma_f32_16x16x32_bf16 v[40:43], v[72:75], v[170:173], v[40:43]
	v_mfma_f32_16x16x32_bf16 v[28:31], v[64:67], v[194:197], v[28:31]
	v_mfma_f32_16x16x32_bf16 v[24:27], v[72:75], v[194:197], v[24:27]
	v_mfma_f32_16x16x32_bf16 v[12:15], v[64:67], v[202:205], v[12:15]
	v_mfma_f32_16x16x32_bf16 v[8:11], v[72:75], v[202:205], v[8:11]
	v_mfma_f32_16x16x32_bf16 v[60:63], v[68:71], v[166:169], v[60:63]
	v_mfma_f32_16x16x32_bf16 v[56:59], v[76:79], v[166:169], v[56:59]
	v_mfma_f32_16x16x32_bf16 v[44:47], v[68:71], v[174:177], v[44:47]
	v_mfma_f32_16x16x32_bf16 v[40:43], v[76:79], v[174:177], v[40:43]
	v_mfma_f32_16x16x32_bf16 v[28:31], v[68:71], v[198:201], v[28:31]
	v_mfma_f32_16x16x32_bf16 v[24:27], v[76:79], v[198:201], v[24:27]
	v_mfma_f32_16x16x32_bf16 v[12:15], v[68:71], v[206:209], v[12:15]
	v_mfma_f32_16x16x32_bf16 v[8:11], v[76:79], v[206:209], v[8:11]
	s_setprio 0
	s_setprio 1
	v_mfma_f32_16x16x32_bf16 v[52:55], v[146:149], v[162:165], v[52:55]
	v_mfma_f32_16x16x32_bf16 v[48:51], v[154:157], v[162:165], v[48:51]
	v_mfma_f32_16x16x32_bf16 v[36:39], v[146:149], v[170:173], v[36:39]
	v_mfma_f32_16x16x32_bf16 v[32:35], v[154:157], v[170:173], v[32:35]
	v_mfma_f32_16x16x32_bf16 v[20:23], v[146:149], v[194:197], v[20:23]
	v_mfma_f32_16x16x32_bf16 v[16:19], v[154:157], v[194:197], v[16:19]
	v_mfma_f32_16x16x32_bf16 v[4:7], v[146:149], v[202:205], v[4:7]
	v_mfma_f32_16x16x32_bf16 v[0:3], v[154:157], v[202:205], v[0:3]
	v_mfma_f32_16x16x32_bf16 v[52:55], v[150:153], v[166:169], v[52:55]
	v_mfma_f32_16x16x32_bf16 v[48:51], v[158:161], v[166:169], v[48:51]
	v_mfma_f32_16x16x32_bf16 v[36:39], v[150:153], v[174:177], v[36:39]
	v_mfma_f32_16x16x32_bf16 v[32:35], v[158:161], v[174:177], v[32:35]
	v_mfma_f32_16x16x32_bf16 v[20:23], v[150:153], v[198:201], v[20:23]
	v_mfma_f32_16x16x32_bf16 v[16:19], v[158:161], v[198:201], v[16:19]
	v_mfma_f32_16x16x32_bf16 v[4:7], v[150:153], v[206:209], v[4:7]
	v_mfma_f32_16x16x32_bf16 v[0:3], v[158:161], v[206:209], v[0:3]
	s_setprio 0
	s_barrier
	s_add_i32 s20, s20, 2
	s_add_u32 s6, s6, 0x100
	s_addc_u32 s7, s7, 0
	s_add_u32 vcc_lo, vcc_lo, 0x100
	s_addc_u32 vcc_hi, vcc_hi, 0
	s_cmp_gt_u32 s20, 29
	s_cbranch_scc0 .LBB0_232
	s_and_b64 vcc, exec, s[60:61]
	s_cbranch_vccz .LBB0_235
	s_barrier
